# mixer first-grab stagger 13.6us (4 x s_sleep 127) for workgroups 256..511 (was 10us)
# speedup vs baseline: 1.0065x; 1.0065x over previous
.LBB0_299:
	s_or_b64 exec, exec, s[4:5]
	v_readlane_b32 s4, v254, 57
	v_readlane_b32 s5, v254, 58
	s_lshl_b32 s90, s4, 4
	s_lshl_b64 s[4:5], s[90:91], 2
	s_add_u32 s4, s42, s4
	s_addc_u32 s5, s43, s5
	v_readlane_b32 s6, v254, 29
	s_add_u32 s6, s4, s6
	s_addc_u32 s7, s5, 0
	v_writelane_b32 v254, s6, 61
	s_barrier
	s_nop 0
	v_writelane_b32 v254, s7, 62
	s_nop 0
	v_readlane_b32 s6, v254, 31
	s_add_u32 s6, s4, s6
	s_addc_u32 s7, s5, 0
	v_writelane_b32 v254, s6, 63
	s_nop 1
	v_writelane_b32 v255, s7, 0
	v_readlane_b32 s6, v254, 33
	s_add_u32 s6, s4, s6
	s_addc_u32 s7, s5, 0
	v_writelane_b32 v255, s6, 1
	s_nop 1
	v_writelane_b32 v255, s7, 2
	v_readlane_b32 s6, v254, 35
	s_add_u32 s6, s4, s6
	s_addc_u32 s7, s5, 0
	v_writelane_b32 v255, s6, 3
	s_nop 1
	v_writelane_b32 v255, s7, 4
	v_readlane_b32 s6, v254, 37
	s_add_u32 s6, s4, s6
	s_addc_u32 s7, s5, 0
	v_writelane_b32 v255, s6, 5
	s_nop 1
	v_writelane_b32 v255, s7, 6
	v_readlane_b32 s6, v254, 39
	s_add_u32 s6, s4, s6
	s_addc_u32 s7, s5, 0
	v_writelane_b32 v255, s6, 7
	s_nop 1
	v_writelane_b32 v255, s7, 8
	v_readlane_b32 s6, v254, 41
	s_add_u32 s6, s4, s6
	s_addc_u32 s7, s5, 0
	v_writelane_b32 v255, s6, 9
	s_nop 1
	v_writelane_b32 v255, s7, 10
	v_readlane_b32 s6, v254, 43
	s_add_u32 s4, s4, s6
	s_addc_u32 s5, s5, 0
	v_writelane_b32 v255, s4, 11
	s_nop 1
	v_writelane_b32 v255, s5, 12
	v_readlane_b32 s6, v254, 13
	s_cmpk_lt_u32 s6, 0x100
	s_cbranch_scc1 .Lmx_nodelay
	s_sleep 127
	s_sleep 127
	s_sleep 127
	s_sleep 127
